# prepass x->bf16: 32 loads per thread issued together, half-wave paired 16-B stores (permlane32_swap)
# baseline (speedup 1.0000x reference)
.LBB0_572:
	s_cmp_lg_u32 s34, 0x100
	s_cbranch_scc1 .Lxc_orig
	s_mov_b64 s[4:5], exec
	v_and_b32_e32 v0, 0x1c0, v34
	v_and_b32_e32 v1, 31, v34
	v_lshl_add_u32 v0, v1, 1, v0
	v_bfe_u32 v6, v34, 5, 1
	v_add_u32_e32 v0, v0, v6
	v_lshl_add_u32 v0, s11, 9, v0
	v_mov_b32_e32 v1, 0
	v_lshl_add_u64 v[2:3], v[0:1], 4, s[44:45]
	v_lshl_add_u64 v[4:5], v[0:1], 3, s[80:81]
	s_mov_b32 s6, 0x200000
	s_mov_b32 s7, 0
	v_mul_u32_u24_e32 v6, 0xffff8, v6
	v_mov_b32_e32 v7, 0
	v_lshl_add_u64 v[4:5], v[4:5], 0, v[6:7]
	global_load_dwordx4 v[36:39], v[2:3], off nt
	v_lshl_add_u64 v[2:3], v[2:3], 0, s[6:7]
	global_load_dwordx4 v[40:43], v[2:3], off nt
	v_lshl_add_u64 v[2:3], v[2:3], 0, s[6:7]
	global_load_dwordx4 v[44:47], v[2:3], off nt
	v_lshl_add_u64 v[2:3], v[2:3], 0, s[6:7]
	global_load_dwordx4 v[48:51], v[2:3], off nt
	v_lshl_add_u64 v[2:3], v[2:3], 0, s[6:7]
	global_load_dwordx4 v[52:55], v[2:3], off nt
	v_lshl_add_u64 v[2:3], v[2:3], 0, s[6:7]
	global_load_dwordx4 v[56:59], v[2:3], off nt
	v_lshl_add_u64 v[2:3], v[2:3], 0, s[6:7]
	global_load_dwordx4 v[60:63], v[2:3], off nt
	v_lshl_add_u64 v[2:3], v[2:3], 0, s[6:7]
	global_load_dwordx4 v[64:67], v[2:3], off nt
	v_lshl_add_u64 v[2:3], v[2:3], 0, s[6:7]
	global_load_dwordx4 v[68:71], v[2:3], off nt
	v_lshl_add_u64 v[2:3], v[2:3], 0, s[6:7]
	global_load_dwordx4 v[72:75], v[2:3], off nt
	v_lshl_add_u64 v[2:3], v[2:3], 0, s[6:7]
	global_load_dwordx4 v[76:79], v[2:3], off nt
	v_lshl_add_u64 v[2:3], v[2:3], 0, s[6:7]
	global_load_dwordx4 v[80:83], v[2:3], off nt
	v_lshl_add_u64 v[2:3], v[2:3], 0, s[6:7]
	global_load_dwordx4 v[84:87], v[2:3], off nt
	v_lshl_add_u64 v[2:3], v[2:3], 0, s[6:7]
	global_load_dwordx4 v[88:91], v[2:3], off nt
	v_lshl_add_u64 v[2:3], v[2:3], 0, s[6:7]
	global_load_dwordx4 v[92:95], v[2:3], off nt
	v_lshl_add_u64 v[2:3], v[2:3], 0, s[6:7]
	global_load_dwordx4 v[96:99], v[2:3], off nt
	v_lshl_add_u64 v[2:3], v[2:3], 0, s[6:7]
	global_load_dwordx4 v[100:103], v[2:3], off nt
	v_lshl_add_u64 v[2:3], v[2:3], 0, s[6:7]
	global_load_dwordx4 v[104:107], v[2:3], off nt
	v_lshl_add_u64 v[2:3], v[2:3], 0, s[6:7]
	global_load_dwordx4 v[108:111], v[2:3], off nt
	v_lshl_add_u64 v[2:3], v[2:3], 0, s[6:7]
	global_load_dwordx4 v[112:115], v[2:3], off nt
	v_lshl_add_u64 v[2:3], v[2:3], 0, s[6:7]
	global_load_dwordx4 v[116:119], v[2:3], off nt
	v_lshl_add_u64 v[2:3], v[2:3], 0, s[6:7]
	global_load_dwordx4 v[120:123], v[2:3], off nt
	v_lshl_add_u64 v[2:3], v[2:3], 0, s[6:7]
	global_load_dwordx4 v[124:127], v[2:3], off nt
	v_lshl_add_u64 v[2:3], v[2:3], 0, s[6:7]
	global_load_dwordx4 v[128:131], v[2:3], off nt
	v_lshl_add_u64 v[2:3], v[2:3], 0, s[6:7]
	global_load_dwordx4 v[132:135], v[2:3], off nt
	v_lshl_add_u64 v[2:3], v[2:3], 0, s[6:7]
	global_load_dwordx4 v[136:139], v[2:3], off nt
	v_lshl_add_u64 v[2:3], v[2:3], 0, s[6:7]
	global_load_dwordx4 v[140:143], v[2:3], off nt
	v_lshl_add_u64 v[2:3], v[2:3], 0, s[6:7]
	global_load_dwordx4 v[144:147], v[2:3], off nt
	v_lshl_add_u64 v[2:3], v[2:3], 0, s[6:7]
	global_load_dwordx4 v[148:151], v[2:3], off nt
	v_lshl_add_u64 v[2:3], v[2:3], 0, s[6:7]
	global_load_dwordx4 v[152:155], v[2:3], off nt
	v_lshl_add_u64 v[2:3], v[2:3], 0, s[6:7]
	global_load_dwordx4 v[156:159], v[2:3], off nt
	v_lshl_add_u64 v[2:3], v[2:3], 0, s[6:7]
	global_load_dwordx4 v[160:163], v[2:3], off nt
	s_waitcnt vmcnt(30)
	v_cvt_pk_bf16_f32 v36, v36, v37
	v_cvt_pk_bf16_f32 v37, v38, v39
	v_cvt_pk_bf16_f32 v38, v40, v41
	v_cvt_pk_bf16_f32 v39, v42, v43
	s_nop 1
	v_permlane32_swap_b32_e32 v36, v38
	v_permlane32_swap_b32_e32 v37, v39
	s_nop 1
	global_store_dwordx4 v[4:5], v[36:39], off
	v_lshl_add_u64 v[4:5], v[4:5], 0, s[6:7]
	s_waitcnt vmcnt(29)
	v_cvt_pk_bf16_f32 v44, v44, v45
	v_cvt_pk_bf16_f32 v45, v46, v47
	v_cvt_pk_bf16_f32 v46, v48, v49
	v_cvt_pk_bf16_f32 v47, v50, v51
	s_nop 1
	v_permlane32_swap_b32_e32 v44, v46
	v_permlane32_swap_b32_e32 v45, v47
	s_nop 1
	global_store_dwordx4 v[4:5], v[44:47], off
	v_lshl_add_u64 v[4:5], v[4:5], 0, s[6:7]
	s_waitcnt vmcnt(28)
	v_cvt_pk_bf16_f32 v52, v52, v53
	v_cvt_pk_bf16_f32 v53, v54, v55
	v_cvt_pk_bf16_f32 v54, v56, v57
	v_cvt_pk_bf16_f32 v55, v58, v59
	s_nop 1
	v_permlane32_swap_b32_e32 v52, v54
	v_permlane32_swap_b32_e32 v53, v55
	s_nop 1
	global_store_dwordx4 v[4:5], v[52:55], off
	v_lshl_add_u64 v[4:5], v[4:5], 0, s[6:7]
	s_waitcnt vmcnt(27)
	v_cvt_pk_bf16_f32 v60, v60, v61
	v_cvt_pk_bf16_f32 v61, v62, v63
	v_cvt_pk_bf16_f32 v62, v64, v65
	v_cvt_pk_bf16_f32 v63, v66, v67
	s_nop 1
	v_permlane32_swap_b32_e32 v60, v62
	v_permlane32_swap_b32_e32 v61, v63
	s_nop 1
	global_store_dwordx4 v[4:5], v[60:63], off
	v_lshl_add_u64 v[4:5], v[4:5], 0, s[6:7]
	s_waitcnt vmcnt(26)
	v_cvt_pk_bf16_f32 v68, v68, v69
	v_cvt_pk_bf16_f32 v69, v70, v71
	v_cvt_pk_bf16_f32 v70, v72, v73
	v_cvt_pk_bf16_f32 v71, v74, v75
	s_nop 1
	v_permlane32_swap_b32_e32 v68, v70
	v_permlane32_swap_b32_e32 v69, v71
	s_nop 1
	global_store_dwordx4 v[4:5], v[68:71], off
	v_lshl_add_u64 v[4:5], v[4:5], 0, s[6:7]
	s_waitcnt vmcnt(25)
	v_cvt_pk_bf16_f32 v76, v76, v77
	v_cvt_pk_bf16_f32 v77, v78, v79
	v_cvt_pk_bf16_f32 v78, v80, v81
	v_cvt_pk_bf16_f32 v79, v82, v83
	s_nop 1
	v_permlane32_swap_b32_e32 v76, v78
	v_permlane32_swap_b32_e32 v77, v79
	s_nop 1
	global_store_dwordx4 v[4:5], v[76:79], off
	v_lshl_add_u64 v[4:5], v[4:5], 0, s[6:7]
	s_waitcnt vmcnt(24)
	v_cvt_pk_bf16_f32 v84, v84, v85
	v_cvt_pk_bf16_f32 v85, v86, v87
	v_cvt_pk_bf16_f32 v86, v88, v89
	v_cvt_pk_bf16_f32 v87, v90, v91
	s_nop 1
	v_permlane32_swap_b32_e32 v84, v86
	v_permlane32_swap_b32_e32 v85, v87
	s_nop 1
	global_store_dwordx4 v[4:5], v[84:87], off
	v_lshl_add_u64 v[4:5], v[4:5], 0, s[6:7]
	s_waitcnt vmcnt(23)
	v_cvt_pk_bf16_f32 v92, v92, v93
	v_cvt_pk_bf16_f32 v93, v94, v95
	v_cvt_pk_bf16_f32 v94, v96, v97
	v_cvt_pk_bf16_f32 v95, v98, v99
	s_nop 1
	v_permlane32_swap_b32_e32 v92, v94
	v_permlane32_swap_b32_e32 v93, v95
	s_nop 1
	global_store_dwordx4 v[4:5], v[92:95], off
	v_lshl_add_u64 v[4:5], v[4:5], 0, s[6:7]
	s_waitcnt vmcnt(22)
	v_cvt_pk_bf16_f32 v100, v100, v101
	v_cvt_pk_bf16_f32 v101, v102, v103
	v_cvt_pk_bf16_f32 v102, v104, v105
	v_cvt_pk_bf16_f32 v103, v106, v107
	s_nop 1
	v_permlane32_swap_b32_e32 v100, v102
	v_permlane32_swap_b32_e32 v101, v103
	s_nop 1
	global_store_dwordx4 v[4:5], v[100:103], off
	v_lshl_add_u64 v[4:5], v[4:5], 0, s[6:7]
	s_waitcnt vmcnt(21)
	v_cvt_pk_bf16_f32 v108, v108, v109
	v_cvt_pk_bf16_f32 v109, v110, v111
	v_cvt_pk_bf16_f32 v110, v112, v113
	v_cvt_pk_bf16_f32 v111, v114, v115
	s_nop 1
	v_permlane32_swap_b32_e32 v108, v110
	v_permlane32_swap_b32_e32 v109, v111
	s_nop 1
	global_store_dwordx4 v[4:5], v[108:111], off
	v_lshl_add_u64 v[4:5], v[4:5], 0, s[6:7]
	s_waitcnt vmcnt(20)
	v_cvt_pk_bf16_f32 v116, v116, v117
	v_cvt_pk_bf16_f32 v117, v118, v119
	v_cvt_pk_bf16_f32 v118, v120, v121
	v_cvt_pk_bf16_f32 v119, v122, v123
	s_nop 1
	v_permlane32_swap_b32_e32 v116, v118
	v_permlane32_swap_b32_e32 v117, v119
	s_nop 1
	global_store_dwordx4 v[4:5], v[116:119], off
	v_lshl_add_u64 v[4:5], v[4:5], 0, s[6:7]
	s_waitcnt vmcnt(19)
	v_cvt_pk_bf16_f32 v124, v124, v125
	v_cvt_pk_bf16_f32 v125, v126, v127
	v_cvt_pk_bf16_f32 v126, v128, v129
	v_cvt_pk_bf16_f32 v127, v130, v131
	s_nop 1
	v_permlane32_swap_b32_e32 v124, v126
	v_permlane32_swap_b32_e32 v125, v127
	s_nop 1
	global_store_dwordx4 v[4:5], v[124:127], off
	v_lshl_add_u64 v[4:5], v[4:5], 0, s[6:7]
	s_waitcnt vmcnt(18)
	v_cvt_pk_bf16_f32 v132, v132, v133
	v_cvt_pk_bf16_f32 v133, v134, v135
	v_cvt_pk_bf16_f32 v134, v136, v137
	v_cvt_pk_bf16_f32 v135, v138, v139
	s_nop 1
	v_permlane32_swap_b32_e32 v132, v134
	v_permlane32_swap_b32_e32 v133, v135
	s_nop 1
	global_store_dwordx4 v[4:5], v[132:135], off
	v_lshl_add_u64 v[4:5], v[4:5], 0, s[6:7]
	s_waitcnt vmcnt(17)
	v_cvt_pk_bf16_f32 v140, v140, v141
	v_cvt_pk_bf16_f32 v141, v142, v143
	v_cvt_pk_bf16_f32 v142, v144, v145
	v_cvt_pk_bf16_f32 v143, v146, v147
	s_nop 1
	v_permlane32_swap_b32_e32 v140, v142
	v_permlane32_swap_b32_e32 v141, v143
	s_nop 1
	global_store_dwordx4 v[4:5], v[140:143], off
	v_lshl_add_u64 v[4:5], v[4:5], 0, s[6:7]
	s_waitcnt vmcnt(16)
	v_cvt_pk_bf16_f32 v148, v148, v149
	v_cvt_pk_bf16_f32 v149, v150, v151
	v_cvt_pk_bf16_f32 v150, v152, v153
	v_cvt_pk_bf16_f32 v151, v154, v155
	s_nop 1
	v_permlane32_swap_b32_e32 v148, v150
	v_permlane32_swap_b32_e32 v149, v151
	s_nop 1
	global_store_dwordx4 v[4:5], v[148:151], off
	v_lshl_add_u64 v[4:5], v[4:5], 0, s[6:7]
	s_waitcnt vmcnt(15)
	v_cvt_pk_bf16_f32 v156, v156, v157
	v_cvt_pk_bf16_f32 v157, v158, v159
	v_cvt_pk_bf16_f32 v158, v160, v161
	v_cvt_pk_bf16_f32 v159, v162, v163
	s_nop 1
	v_permlane32_swap_b32_e32 v156, v158
	v_permlane32_swap_b32_e32 v157, v159
	s_nop 1
	global_store_dwordx4 v[4:5], v[156:159], off
	s_branch .LBB0_579
